# XCD-local seam split: arrive with a returning atomic at phase end, collect it after the next phase's scalar set-up right before the first cross-workgroup load
# speedup vs baseline: 1.0207x; 1.0207x over previous
.LBB0_29:
	s_lshl_b32 s0, s12, 5
	s_add_i32 s6, s0, s13
	s_cmp_lg_u32 s14, 0
	s_cselect_b64 s[0:1], -1, 0
	s_and_b64 s[0:1], s[0:1], exec
	s_cselect_b32 s8, s6, s3
	s_lshl_b32 s0, s8, 6
	s_and_b32 s0, s0, 0xfffff800
	s_add_i32 s1, s0, 0x800
	s_cmp_lg_u32 s14, 0
	s_cselect_b64 s[6:7], -1, 0
	s_and_b64 s[6:7], s[6:7], exec
	s_cselect_b32 s98, s1, 0x4000
	s_lshl_b32 s10, s62, 3
	s_cmp_lg_u32 s14, 0
	s_cselect_b64 s[6:7], -1, 0
	s_and_b64 s[6:7], s[6:7], exec
	s_cselect_b32 s64, 0x100, s10
	s_lshl_b32 s1, s8, 4
	s_and_b32 s1, s1, 0xfffffe00
	s_add_i32 s3, s1, 0x200
	s_cmp_lg_u32 s14, 0
	s_cselect_b64 s[6:7], -1, 0
	s_and_b64 s[6:7], s[6:7], exec
	s_cselect_b32 s99, s3, 0x1000
	s_lshl_b32 s3, s13, 3
	s_add_i32 s3, s3, s12
	s_cmp_lg_u32 s14, 0
	s_cselect_b64 s[6:7], -1, 0
	v_writelane_b32 v236, s6, 8
	s_mov_b32 s36, 2.0
	s_mov_b32 s88, 0x41900000
	v_writelane_b32 v236, s7, 9
	s_and_b64 s[6:7], s[6:7], exec
	s_cselect_b32 s7, s3, s2
	s_lshl_b32 s9, s8, 3
	s_add_u32 s2, s60, 0x5300000
	s_addc_u32 s3, s61, 0
	v_writelane_b32 v236, s2, 10
	s_mov_b32 s96, 0x41a00000
	s_mov_b32 s44, 0x42480000
	v_writelane_b32 v236, s3, 11
	s_add_u32 s2, s60, 0x7300000
	s_addc_u32 s3, s61, 0
	s_add_u32 s90, s60, 0xd300000
	s_addc_u32 s91, s61, 0
	s_add_u32 s92, s60, 0xf300000
	s_addc_u32 s93, s61, 0
	s_add_u32 s94, s60, 0x9300000
	v_writelane_b32 v236, s2, 12
	s_addc_u32 s95, s61, 0
	s_mov_b32 s84, 0x42000000
	v_writelane_b32 v236, s3, 13
	s_add_u32 s2, s60, 0x100000
	s_addc_u32 s3, s61, 0
	v_writelane_b32 v236, s2, 14
	v_mbcnt_lo_u32_b32 v0, -1, 0
	v_mov_b32_e32 v97, 0
	v_writelane_b32 v236, s3, 15
	s_add_u32 s2, s74, 0xb000
	s_addc_u32 s3, s75, 0
	v_writelane_b32 v236, s2, 16
	v_mov_b32_e32 v153, 0x358637bd
	v_mov_b32_e32 v154, 0x260
	v_writelane_b32 v236, s3, 17
	s_add_u32 s2, s60, 0x3d80000
	s_addc_u32 s3, s61, 0
	v_writelane_b32 v236, s2, 18
	s_mov_b32 s37, 0x40400000
	s_mov_b32 s89, 0x41980000
	v_writelane_b32 v236, s3, 19
	s_add_u32 s2, s60, 0x2200000
	s_addc_u32 s3, s61, 0
	v_writelane_b32 v236, s2, 20
	s_mov_b32 s97, 0x41a80000
	s_mov_b32 s45, 0x424c0000
	v_writelane_b32 v236, s3, 21
	s_add_u32 s2, s74, 0x9000
	s_addc_u32 s3, s75, 0
	v_writelane_b32 v236, s2, 22
	s_mov_b32 s85, 0x42040000
	v_mov_b32_e32 v155, 1
	v_writelane_b32 v236, s3, 23
	s_add_u32 s2, s60, 0x5100000
	s_addc_u32 s3, s61, 0
	v_writelane_b32 v236, s2, 24
	v_mbcnt_hi_u32_b32 v156, -1, v0
	v_mov_b32_e32 v157, 0x42800000
	v_writelane_b32 v236, s3, 25
	s_add_u32 s2, s60, 0x4f00000
	s_addc_u32 s3, s61, 0
	v_writelane_b32 v236, s2, 26
	v_mov_b32_e32 v158, 0xff800000
	s_nop 0
	v_writelane_b32 v236, s3, 27
	s_add_u32 s2, s74, 0x7000
	s_addc_u32 s3, s75, 0
	v_writelane_b32 v236, s2, 28
	s_nop 1
	v_writelane_b32 v236, s3, 29
	s_add_u32 s2, s60, 0x3800000
	s_addc_u32 s3, s61, 0
	v_writelane_b32 v236, s2, 30
	s_nop 1
	v_writelane_b32 v236, s3, 31
	s_add_u32 s2, s60, 0x1700000
	s_addc_u32 s3, s61, 0
	s_add_u32 s20, s60, 0xb300000
	v_writelane_b32 v236, s2, 32
	s_addc_u32 s21, s61, 0
	s_nop 0
	v_writelane_b32 v236, s3, 33
	s_add_u32 s2, s60, 0x4d00000
	s_addc_u32 s3, s61, 0
	v_writelane_b32 v236, s2, 34
	s_nop 1
	v_writelane_b32 v236, s3, 35
	s_add_u32 s2, s60, 0x4b00000
	s_addc_u32 s3, s61, 0
	v_writelane_b32 v236, s2, 36
	s_nop 1
	v_writelane_b32 v236, s3, 37
	s_add_u32 s2, s74, 0x5000
	s_addc_u32 s3, s75, 0
	v_writelane_b32 v236, s2, 38
	s_nop 1
	v_writelane_b32 v236, s3, 39
	s_add_u32 s2, s60, 0x3280000
	s_addc_u32 s3, s61, 0
	v_writelane_b32 v236, s2, 40
	s_nop 1
	v_writelane_b32 v236, s3, 41
	s_add_u32 s2, s60, 0xc00000
	s_addc_u32 s3, s61, 0
	v_writelane_b32 v236, s2, 42
	s_nop 1
	v_writelane_b32 v236, s3, 43
	s_add_u32 s2, s74, 0x3000
	s_addc_u32 s3, s75, 0
	v_writelane_b32 v236, s2, 44
	s_nop 1
	v_writelane_b32 v236, s3, 45
	s_add_u32 s2, s60, 0x4900000
	s_addc_u32 s3, s61, 0
	v_writelane_b32 v236, s2, 46
	s_nop 1
	v_writelane_b32 v236, s3, 47
	s_add_u32 s2, s60, 0x4300000
	s_addc_u32 s3, s61, 0
	v_writelane_b32 v236, s2, 48
	s_nop 1
	v_writelane_b32 v236, s3, 49
	s_add_u32 s2, s74, 0x1000
	s_addc_u32 s3, s75, 0
	v_writelane_b32 v236, s2, 50
	s_nop 1
	v_writelane_b32 v236, s3, 51
	s_add_u32 s2, s60, 0x2d00000
	s_addc_u32 s3, s61, 0
	v_writelane_b32 v236, s2, 52
	s_nop 1
	v_writelane_b32 v236, s3, 53
	s_add_u32 s2, s74, 0x2000
	s_addc_u32 s3, s75, 0
	v_writelane_b32 v236, s2, 54
	s_cmp_lg_u64 s[74:75], 0
	s_nop 0
	v_writelane_b32 v236, s3, 55
	s_cselect_b64 s[2:3], -1, 0
	v_writelane_b32 v236, s2, 56
	s_cmpk_eq_i32 s62, 0x100
	s_nop 0
	v_writelane_b32 v236, s3, 57
	s_cselect_b64 s[2:3], -1, 0
	v_writelane_b32 v236, s2, 58
	s_cmpk_lg_i32 s62, 0x100
	s_nop 0
	v_writelane_b32 v236, s3, 59
	s_cselect_b64 s[2:3], -1, 0
	v_writelane_b32 v236, s2, 60
	s_nop 1
	v_writelane_b32 v236, s3, 61
	s_add_u32 s2, s72, 0xb00000
	s_addc_u32 s3, s73, 0
	v_writelane_b32 v236, s2, 62
	s_nop 1
	v_writelane_b32 v236, s3, 63
	s_add_u32 s2, s70, 0x1600000
	s_addc_u32 s3, s71, 0
	v_writelane_b32 v235, s2, 0
	v_readlane_b32 s24, v236, 0
	v_readlane_b32 s30, v236, 6
	v_writelane_b32 v235, s3, 1
	s_add_u32 s2, s74, 0x4000
	s_addc_u32 s3, s75, 0
	v_writelane_b32 v235, s2, 2
	v_readlane_b32 s31, v236, 7
	v_readlane_b32 s25, v236, 1
	v_writelane_b32 v235, s3, 3
	s_add_u32 s2, s74, 0x8000
	s_addc_u32 s3, s75, 0
	v_writelane_b32 v235, s2, 4
	v_readlane_b32 s26, v236, 2
	v_readlane_b32 s27, v236, 3
	v_writelane_b32 v235, s3, 5
	s_add_u32 s2, s72, 0x1600000
	s_addc_u32 s3, s73, 0
	v_writelane_b32 v235, s2, 6
	v_readlane_b32 s28, v236, 4
	v_readlane_b32 s29, v236, 5
	v_writelane_b32 v235, s3, 7
	s_add_u32 s2, s70, 0x2c00000
	s_addc_u32 s3, s71, 0
	v_writelane_b32 v235, s2, 8
	s_mov_b32 s24, 0x40c00000
	s_mov_b32 s26, 0x42400000
	v_writelane_b32 v235, s3, 9
	s_add_u32 s2, s74, 0x6000
	s_addc_u32 s3, s75, 0
	v_writelane_b32 v235, s2, 10
	s_cmp_lg_u64 s[82:83], 0
	s_mov_b32 s28, 0x42180000
	v_writelane_b32 v235, s3, 11
	s_cselect_b64 s[2:3], -1, 0
	v_writelane_b32 v235, s2, 12
	s_mov_b32 s25, 0x40e00000
	s_mov_b32 s27, 0x42440000
	v_writelane_b32 v235, s3, 13
	s_add_u32 s2, s72, 0x2100000
	s_addc_u32 s3, s73, 0
	v_writelane_b32 v235, s2, 14
	s_mov_b32 s29, 0x421c0000
	s_nop 0
	v_writelane_b32 v235, s3, 15
	s_add_u32 s2, s70, 0x4200000
	s_addc_u32 s3, s71, 0
	v_writelane_b32 v235, s2, 16
	s_nop 1
	v_writelane_b32 v235, s3, 17
	s_add_u32 s2, s74, 0xa000
	s_addc_u32 s3, s75, 0
	v_writelane_b32 v235, s2, 18
	s_cmp_lg_u64 s[30:31], 0
	s_mov_b32 s30, 0x41800000
	v_writelane_b32 v235, s3, 19
	s_cselect_b64 s[2:3], -1, 0
	v_writelane_b32 v235, s2, 20
	s_mov_b32 s31, 0x41880000
	s_nop 0
	v_writelane_b32 v235, s3, 21
	s_add_u32 s2, s60, 0x12c00000
	v_writelane_b32 v235, s2, 22
	s_addc_u32 s2, s61, 0
	s_cmp_eq_u64 s[68:69], 0
	v_writelane_b32 v235, s2, 23
	s_cselect_b64 s[2:3], -1, 0
	s_cmp_lg_u64 s[68:69], 0
	s_cselect_b64 s[14:15], -1, 0
	v_writelane_b32 v235, s14, 24
	s_cmpk_lt_i32 s8, 0x100
	s_nop 0
	v_writelane_b32 v235, s15, 25
	v_writelane_b32 v235, s8, 26
	s_cselect_b64 s[14:15], -1, 0
	v_writelane_b32 v235, s14, 27
	s_and_b32 s6, s9, 0xf8
	s_or_b32 s1, s1, s6
	v_writelane_b32 v235, s15, 28
	v_writelane_b32 v235, s1, 29
	s_or_b32 s0, s0, s6
	v_writelane_b32 v235, s0, 30
	s_ashr_i32 s0, s7, 31
	v_writelane_b32 v235, s0, 31
	s_lshr_b32 s0, s0, 29
	s_add_i32 s0, s7, s0
	s_ashr_i32 s1, s0, 3
	s_and_b32 s0, s0, -8
	s_sub_i32 s8, s7, s0
	s_ashr_i32 s0, s62, 31
	v_writelane_b32 v235, s1, 32
	s_cmpk_gt_i32 s7, 0x7f
	v_writelane_b32 v235, s0, 33
	s_cselect_b64 s[0:1], -1, 0
	v_writelane_b32 v235, s0, 34
	s_nop 1
	v_writelane_b32 v235, s1, 35
	s_lshl_b32 s0, s7, 3
	s_addk_i32 s0, 0xfc00
	s_add_u32 s14, s60, 0x12b00200
	s_addc_u32 s15, s61, 0
	s_add_u32 s52, s60, 0x12b00400
	s_addc_u32 s53, s61, 0
	s_add_u32 s54, s60, 0x12b00500
	s_addc_u32 s55, s61, 0
	s_add_u32 s66, s60, 0x12b00600
	s_addc_u32 s67, s61, 0
	s_add_u32 s16, s60, 0x12b00700
	s_addc_u32 s17, s61, 0
	s_add_u32 s18, s60, 0x12b00800
	s_addc_u32 s19, s61, 0
	s_add_u32 s22, s60, 0x12b00900
	v_writelane_b32 v235, s7, 36
	s_addc_u32 s23, s61, 0
	v_writelane_b32 v235, s0, 37
	s_add_u32 s0, s60, 0x12b00a00
	s_addc_u32 s1, s61, 0
	v_writelane_b32 v235, s0, 38
	s_nop 1
	v_writelane_b32 v235, s1, 39
	s_add_u32 s0, s60, 0x12b00b00
	s_addc_u32 s1, s61, 0
	v_writelane_b32 v235, s0, 40
	s_nop 1
	v_writelane_b32 v235, s1, 41
	s_add_u32 s0, s60, 0x12b00c00
	s_addc_u32 s1, s61, 0
	v_writelane_b32 v235, s0, 42
	s_nop 1
	v_writelane_b32 v235, s1, 43
	s_add_u32 s0, s60, 0x12b00d00
	s_addc_u32 s1, s61, 0
	v_writelane_b32 v235, s0, 44
	s_nop 1
	v_writelane_b32 v235, s1, 45
	s_add_u32 s0, s60, 0x12b00e00
	s_addc_u32 s1, s61, 0
	v_writelane_b32 v235, s0, 46
	s_nop 1
	v_writelane_b32 v235, s1, 47
	s_add_u32 s0, s60, 0x12b00f00
	s_addc_u32 s1, s61, 0
	v_writelane_b32 v235, s0, 48
	s_nop 1
	v_writelane_b32 v235, s1, 49
	s_add_u32 s0, s60, 0x12b01000
	s_addc_u32 s1, s61, 0
	v_writelane_b32 v235, s0, 50
	s_nop 1
	v_writelane_b32 v235, s1, 51
	s_add_u32 s0, s60, 0x12b01100
	s_addc_u32 s1, s61, 0
	v_writelane_b32 v235, s0, 52
	s_nop 1
	v_writelane_b32 v235, s1, 53
	s_add_u32 s0, s60, 0x12b01200
	s_addc_u32 s1, s61, 0
	v_writelane_b32 v235, s0, 54
	s_nop 1
	v_writelane_b32 v235, s1, 55
	s_add_u32 s0, s60, 0x12b01300
	s_addc_u32 s1, s61, 0
	v_writelane_b32 v235, s0, 56
	s_cmp_eq_u32 s50, 15
	s_nop 0
	v_writelane_b32 v235, s1, 57
	s_cselect_b64 s[0:1], -1, 0
	v_writelane_b32 v235, s0, 58
	s_cmp_eq_u32 s50, 14
	s_nop 0
	v_writelane_b32 v235, s1, 59
	s_cselect_b64 s[0:1], -1, 0
	v_writelane_b32 v235, s0, 60
	s_cmp_eq_u32 s50, 13
	s_nop 0
	v_writelane_b32 v235, s1, 61
	s_cselect_b64 s[0:1], -1, 0
	v_writelane_b32 v235, s0, 62
	s_cmp_eq_u32 s50, 12
	s_nop 0
	v_writelane_b32 v235, s1, 63
	s_cselect_b64 s[0:1], -1, 0
	v_writelane_b32 v234, s0, 0
	s_cmp_eq_u32 s50, 11
	s_nop 0
	v_writelane_b32 v234, s1, 1
	s_cselect_b64 s[0:1], -1, 0
	v_writelane_b32 v234, s0, 2
	s_cmp_eq_u32 s50, 10
	s_nop 0
	v_writelane_b32 v234, s1, 3
	s_cselect_b64 s[0:1], -1, 0
	v_writelane_b32 v234, s0, 4
	s_cmp_eq_u32 s50, 9
	s_nop 0
	v_writelane_b32 v234, s1, 5
	s_cselect_b64 s[0:1], -1, 0
	v_writelane_b32 v234, s0, 6
	s_cmp_eq_u32 s50, 8
	s_nop 0
	v_writelane_b32 v234, s1, 7
	s_cselect_b64 s[0:1], -1, 0
	v_writelane_b32 v234, s0, 8
	s_cmp_eq_u32 s50, 7
	s_nop 0
	v_writelane_b32 v234, s1, 9
	s_cselect_b64 s[0:1], -1, 0
	v_writelane_b32 v234, s0, 10
	s_cmp_eq_u32 s50, 6
	s_nop 0
	v_writelane_b32 v234, s1, 11
	s_cselect_b64 s[0:1], -1, 0
	v_writelane_b32 v234, s0, 12
	s_cmp_eq_u32 s50, 5
	s_nop 0
	v_writelane_b32 v234, s1, 13
	s_cselect_b64 s[0:1], -1, 0
	v_writelane_b32 v234, s0, 14
	s_cmp_eq_u32 s50, 4
	s_nop 0
	v_writelane_b32 v234, s1, 15
	s_cselect_b64 s[0:1], -1, 0
	v_writelane_b32 v234, s0, 16
	s_cmp_eq_u32 s50, 3
	s_nop 0
	v_writelane_b32 v234, s1, 17
	s_cselect_b64 s[0:1], -1, 0
	v_writelane_b32 v234, s0, 18
	s_cmp_eq_u32 s50, 2
	s_nop 0
	v_writelane_b32 v234, s1, 19
	s_cselect_b64 s[0:1], -1, 0
	v_writelane_b32 v234, s0, 20
	s_cmp_eq_u32 s50, 1
	s_nop 0
	v_writelane_b32 v234, s1, 21
	s_cselect_b64 s[0:1], -1, 0
	v_writelane_b32 v234, s0, 22
	s_cmp_eq_u32 s50, 0
	s_nop 0
	v_writelane_b32 v234, s1, 23
	s_cselect_b64 s[0:1], -1, 0
	v_writelane_b32 v234, s0, 24
	s_nop 1
	v_writelane_b32 v234, s1, 25
	s_lshl_b32 s0, s50, 8
	s_add_u32 s0, s4, s0
	s_addc_u32 s1, s5, 0
	s_add_u32 s6, s0, 0x1400
	s_addc_u32 s7, s1, 0
	v_writelane_b32 v234, s6, 26
	s_add_u32 s0, s0, 0x2400
	s_addc_u32 s1, s1, 0
	v_writelane_b32 v234, s7, 27
	v_writelane_b32 v234, s0, 28
	s_mov_b64 s[50:51], s[14:15]
	s_mov_b32 s14, 4.0
	v_writelane_b32 v234, s1, 29
	s_add_u32 s0, s60, 0x12b03400
	s_addc_u32 s1, s61, 0
	v_writelane_b32 v234, s0, 30
	s_mov_b32 s15, 0x40a00000
	s_nop 0
	v_writelane_b32 v234, s1, 31
	s_add_u32 s0, s60, 0x12b03500
	s_addc_u32 s1, s61, 0
	s_lshl_b32 s6, s12, 6
	v_writelane_b32 v234, s0, 32
	s_add_i32 s46, s6, 0x1000
	s_mov_b64 s[12:13], 0x80
	v_writelane_b32 v234, s1, 33
	s_lshl_b64 s[0:1], s[46:47], 2
	s_add_u32 s0, s4, s0
	s_addc_u32 s1, s5, s1
	v_writelane_b32 v234, s0, 34
	s_add_i32 s46, s6, 0x1400
	s_nop 0
	v_writelane_b32 v234, s1, 35
	s_lshl_b64 s[0:1], s[46:47], 2
	s_add_u32 s0, s4, s0
	s_addc_u32 s1, s5, s1
	v_writelane_b32 v234, s0, 36
	s_ashr_i32 s11, s10, 31
	s_nop 0
	v_writelane_b32 v234, s1, 37
	s_mul_i32 s0, s63, s62
	s_mul_i32 s0, s0, s33
	v_writelane_b32 v234, s0, 38
	v_writelane_b32 v234, s8, 39
	s_lshr_b32 s0, s8, 31
	v_writelane_b32 v234, s0, 40
	s_add_i32 s0, s9, s10
	v_writelane_b32 v234, s0, 41
	s_lshl_b64 s[0:1], s[10:11], 2
	v_writelane_b32 v234, s0, 42
	s_mov_b32 s33, 0xf800000
	s_nop 0
	v_writelane_b32 v234, s1, 43
	s_lshl_b64 s[0:1], s[10:11], 11
	v_writelane_b32 v234, s0, 44
	s_nop 1
	v_writelane_b32 v234, s1, 45
	s_add_u32 s0, s68, 0x800
	v_writelane_b32 v234, s0, 46
	v_writelane_b32 v234, s68, 47
	s_addc_u32 s0, s69, 0
	s_nop 0
	v_writelane_b32 v234, s69, 48
	v_writelane_b32 v234, s70, 49
	v_writelane_b32 v234, s71, 50
	v_writelane_b32 v234, s72, 51
	v_writelane_b32 v234, s73, 52
	v_writelane_b32 v234, s74, 53
	v_writelane_b32 v234, s75, 54
	v_writelane_b32 v234, s76, 55
	v_writelane_b32 v234, s77, 56
	v_writelane_b32 v234, s78, 57
	v_writelane_b32 v234, s79, 58
	v_writelane_b32 v234, s80, 59
	v_writelane_b32 v234, s81, 60
	v_writelane_b32 v234, s82, 61
	v_writelane_b32 v234, s83, 62
	v_writelane_b32 v234, s0, 63
	s_lshl_b64 s[0:1], s[10:11], 12
	v_writelane_b32 v233, s0, 0
	s_mov_b32 s70, s9
	s_mov_b64 s[68:69], s[10:11]
	v_writelane_b32 v233, s1, 1
	s_add_u32 s0, s60, 0xb300080
	v_writelane_b32 v233, s0, 2
	s_addc_u32 s0, s61, 0
	v_writelane_b32 v233, s0, 3
	s_add_u32 s0, s60, 0x9320000
	s_mov_b64 s[4:5], s[56:57]
	v_writelane_b32 v233, s0, 4
	s_mov_b64 s[6:7], s[58:59]
	s_mov_b64 s[8:9], s[60:61]
	s_mov_b32 s10, s62
	v_writelane_b32 v233, s4, 5
	s_addc_u32 s0, s61, 0
	s_ashr_i32 s65, s64, 31
	v_writelane_b32 v233, s5, 6
	v_writelane_b32 v233, s6, 7
	v_writelane_b32 v233, s7, 8
	v_writelane_b32 v233, s8, 9
	v_writelane_b32 v233, s9, 10
	v_writelane_b32 v233, s10, 11
	v_writelane_b32 v233, s11, 12
	v_writelane_b32 v233, s0, 13
	s_lshl_b32 s0, s64, 2
	v_writelane_b32 v233, s0, 14
	s_lshl_b32 s0, s64, 9
	v_writelane_b32 v233, s0, 15
	s_add_i32 s0, 0, 0x20040
	v_writelane_b32 v233, s0, 16
	s_add_i32 s0, 0, 0x20044
	v_writelane_b32 v233, s0, 17
	s_lshl_b64 s[8:9], s[64:65], 2
	v_writelane_b32 v233, s8, 18
	s_mov_b32 s1, 0
	s_mov_b32 s0, s68
	v_writelane_b32 v233, s9, 19
	s_lshl_b64 s[8:9], s[64:65], 11
	v_writelane_b32 v233, s8, 20
	s_mov_b64 s[76:77], s[16:17]
	s_mov_b64 s[78:79], s[18:19]
	v_writelane_b32 v233, s9, 21
	s_lshl_b64 s[8:9], s[64:65], 12
	v_writelane_b32 v233, s8, 22
	s_mov_b64 s[82:83], s[22:23]
	s_mov_b32 s6, 0x41b00000
	v_writelane_b32 v233, s9, 23
	s_lshl_b64 s[8:9], s[64:65], 6
	v_writelane_b32 v233, s8, 24
	s_mov_b32 s18, 0x42580000
	s_mov_b32 s22, 0x42500000
	v_writelane_b32 v233, s9, 25
	v_writelane_b32 v233, s86, 26
	s_mov_b32 s4, 0x42100000
	s_mov_b32 s10, 0x42080000
	v_writelane_b32 v233, s87, 27
	v_writelane_b32 v233, s98, 28
	v_writelane_b32 v233, s0, 29
	s_mov_b32 s7, 0x41b80000
	s_mov_b32 s19, 0x425c0000
	v_writelane_b32 v233, s1, 30
	s_mov_b32 s0, s64
	v_writelane_b32 v233, s0, 31
	s_mov_b32 s23, 0x42540000
	s_mov_b32 s5, 0x42140000
	v_writelane_b32 v233, s1, 32
	v_writelane_b32 v233, s99, 33
	v_writelane_b32 v233, s70, 34
	v_writelane_b32 v233, s50, 35
	s_mov_b32 s11, 0x420c0000
	s_movk_i32 s81, 0x7fff
	v_writelane_b32 v233, s51, 36
	v_writelane_b32 v233, s52, 37
	s_mov_b32 s71, 0xffff0000
	s_movk_i32 s80, 0x48
	v_writelane_b32 v233, s53, 38
	v_writelane_b32 v233, s54, 39
	s_mov_b64 s[16:17], 0x20000
	s_nop 0
	v_writelane_b32 v233, s55, 40
	v_writelane_b32 v233, s66, 41
	s_nop 1
	v_writelane_b32 v233, s67, 42
	v_writelane_b32 v233, s76, 43
	s_nop 1
	v_writelane_b32 v233, s77, 44
	v_writelane_b32 v233, s78, 45
	s_nop 1
	v_writelane_b32 v233, s79, 46
	v_writelane_b32 v233, s82, 47
	s_nop 1
	v_writelane_b32 v233, s83, 48
	s_mov_b32 s0, 0
	v_writelane_b32 v232, s0, 58
	s_branch .LBB0_31

.LBB0_320:
	s_andn2_b64 vcc, exec, s[0:1]
	s_cbranch_vccnz .LBB0_399
	v_bfe_i32 v2, v12, 27, 1
	v_lshlrev_b32_e32 v0, 4, v12
	v_lshrrev_b32_e32 v2, 22, v2
	v_add_u32_e32 v2, v0, v2
	v_and_b32_e32 v2, 0xfffffc00, v2
	v_sub_u32_e32 v2, v0, v2
	v_ashrrev_i32_e32 v1, 31, v12
	s_waitcnt lgkmcnt(0)
	v_lshrrev_b32_e32 v3, 4, v2
	v_lshrrev_b32_e32 v1, 26, v1
	v_bitop3_b32 v2, v3, v2, 32 bitop3:0x6c
	v_add_u32_e32 v1, v12, v1
	v_ashrrev_i32_e32 v4, 31, v2
	v_ashrrev_i32_e32 v1, 6, v1
	v_lshrrev_b32_e32 v4, 26, v4
	v_lshlrev_b32_e32 v3, 3, v1
	v_add_u32_e32 v4, v2, v4
	v_and_b32_e32 v3, -16, v3
	v_ashrrev_i32_e32 v5, 6, v4
	v_lshlrev_b32_e32 v1, 5, v1
	v_add_u32_e32 v3, v5, v3
	v_and_b32_e32 v13, 32, v1
	v_and_b32_e32 v1, 0xc0, v4
	v_sub_u32_e32 v1, v2, v1
	v_lshlrev_b32_e32 v2, 1, v3
	v_lshrrev_b32_e32 v4, 2, v3
	v_and_b32_e32 v5, 3, v5
	s_mov_b32 s1, 0x7fffffe0
	v_ashrrev_i16_sdwa v1, v155, sext(v1) dst_sel:DWORD dst_unused:UNUSED_PAD src0_sel:DWORD src1_sel:BYTE_0
	v_and_b32_e32 v2, 24, v2
	v_and_b32_e32 v4, 4, v4
	v_and_or_b32 v5, v3, s1, v5
	v_bfe_i32 v14, v1, 0, 16
	v_or3_b32 v2, v5, v4, v2
	v_readlane_b32 s52, v233, 50
	v_add_u32_e32 v1, v13, v14
	v_add_u32_e32 v0, 0x2000, v0
	v_mul_lo_u32 v15, v3, s52
	v_mul_lo_u32 v2, v2, s52
	v_add_lshl_u32 v130, v1, v15, 1
	v_add_lshl_u32 v96, v2, v1, 1
	v_ashrrev_i32_e32 v1, 31, v0
	v_lshrrev_b32_e32 v1, 22, v1
	v_add_u32_e32 v1, v0, v1
	v_ashrrev_i32_e32 v1, 10, v1
	v_readlane_b32 s53, v233, 51
	v_mul_i32_i24_e32 v2, 0x400, v1
	v_sub_u32_e32 v0, v0, v2
	s_mov_b32 s53, s47
	v_lshrrev_b32_e32 v2, 4, v0
	s_lshl_b64 s[72:73], s[52:53], 9
	s_ashr_i32 s9, s46, 31
	v_bitop3_b32 v0, v2, v0, 32 bitop3:0x6c
	s_mul_i32 s9, s72, s9
	s_mul_hi_u32 s39, s72, s46
	v_ashrrev_i32_e32 v3, 31, v0
	s_add_i32 s9, s39, s9
	s_lshr_b32 s39, s52, 23
	v_writelane_b32 v232, s76, 22
	v_lshrrev_b32_e32 v3, 26, v3
	s_mul_i32 s40, s39, s46
	v_writelane_b32 v232, s77, 23
	v_lshlrev_b32_e32 v2, 3, v1
	v_add_u32_e32 v3, v0, v3
	s_add_i32 s43, s9, s40
	s_ashr_i32 s9, s69, 31
	v_writelane_b32 v232, s78, 24
	v_and_b32_e32 v2, -16, v2
	v_ashrrev_i32_e32 v4, 6, v3
	s_mul_i32 s9, s72, s9
	s_mul_hi_u32 s40, s72, s69
	v_writelane_b32 v232, s79, 25
	s_ashr_i32 s0, s38, 6
	v_add_u32_e32 v2, v4, v2
	v_lshlrev_b32_e32 v1, 5, v1
	v_and_b32_e32 v4, 3, v4
	s_add_i32 s9, s40, s9
	s_mul_i32 s39, s39, s69
	v_and_b32_e32 v16, 32, v1
	v_and_b32_e32 v1, 0xc0, v3
	v_and_or_b32 v4, v2, s1, v4
	s_ashr_i32 s1, s38, 8
	s_lshl_b64 s[34:35], s[52:53], 8
	s_lshl_b32 s8, s0, 10
	s_add_i32 s9, s9, s39
	s_mul_i32 s39, s72, s69
	v_readlane_b32 s40, v232, 11
	v_sub_u32_e32 v0, v0, v1
	v_lshlrev_b32_e32 v1, 1, v2
	v_lshrrev_b32_e32 v3, 2, v2
	v_readlane_b32 s41, v232, 12
	s_add_u32 s78, s40, s39
	v_ashrrev_i16_sdwa v0, v155, sext(v0) dst_sel:DWORD dst_unused:UNUSED_PAD src0_sel:DWORD src1_sel:BYTE_0
	v_and_b32_e32 v1, 24, v1
	v_and_b32_e32 v3, 4, v3
	s_addc_u32 s79, s41, s9
	s_add_i32 s9, s8, 0
	v_bfe_i32 v17, v0, 0, 16
	v_or3_b32 v1, v4, v3, v1
	v_readlane_b32 vcc_lo, v232, 58
	s_cmp_eq_u32 vcc_lo, 0
	s_cbranch_scc1 .Lsb_done_g
	v_readfirstlane_b32 vcc_hi, v152
	s_cmp_lt_u32 vcc_hi, 64
	s_cbranch_scc0 .Lsb_wait_g
	s_waitcnt vmcnt(0)
	v_readfirstlane_b32 vcc_lo, v210
	s_and_b32 vcc_hi, vcc_lo, 31
	s_cmp_eq_u32 vcc_hi, 31
	s_cbranch_scc1 .Lsb_got_g
	s_or_b32 vcc_lo, vcc_lo, 31
	s_add_u32 vcc_lo, vcc_lo, 1
	v_mov_b32_e32 v211, vcc_lo
	v_readlane_b32 s100, v234, 34
	v_readlane_b32 s101, v234, 35
	s_mov_b32 m0, 0
	s_nop 4

.LBB0_486:
	s_and_b64 vcc, exec, s[0:1]
	s_cbranch_vccz .LBB0_511
	v_readlane_b32 s0, v235, 30
	v_readlane_b32 s1, v232, 21
	s_add_i32 s8, s0, s1
	v_readlane_b32 s0, v236, 8
	v_readlane_b32 s1, v236, 9
	s_and_b64 s[0:1], s[0:1], exec
	s_cselect_b32 s8, s8, s76
	s_cmp_ge_i32 s8, s98
	s_cbranch_scc1 .LBB0_511
	v_readlane_b32 vcc_lo, v232, 58
	s_cmp_eq_u32 vcc_lo, 0
	s_cbranch_scc1 .Lsb_done_r
	v_readfirstlane_b32 vcc_hi, v152
	s_cmp_lt_u32 vcc_hi, 64
	s_cbranch_scc0 .Lsb_wait_r
	s_waitcnt vmcnt(0)
	v_readfirstlane_b32 vcc_lo, v210
	s_and_b32 vcc_hi, vcc_lo, 31
	s_cmp_eq_u32 vcc_hi, 31
	s_cbranch_scc1 .Lsb_got_r
	s_or_b32 vcc_lo, vcc_lo, 31
	s_add_u32 vcc_lo, vcc_lo, 1
	v_mov_b32_e32 v211, vcc_lo
	v_readlane_b32 s100, v234, 34
	v_readlane_b32 s101, v234, 35
	s_mov_b32 m0, 0
	s_nop 4

.LBB0_511:
	v_readlane_b32 vcc_lo, v232, 58
	s_cmp_eq_u32 vcc_lo, 0
	s_cbranch_scc1 .Lsb_done_e
	v_readfirstlane_b32 vcc_hi, v152
	s_cmp_lt_u32 vcc_hi, 64
	s_cbranch_scc0 .Lsb_wait_e
	s_waitcnt vmcnt(0)
	v_readfirstlane_b32 vcc_lo, v210
	s_and_b32 vcc_hi, vcc_lo, 31
	s_cmp_eq_u32 vcc_hi, 31
	s_cbranch_scc1 .Lsb_got_e
	s_or_b32 vcc_lo, vcc_lo, 31
	s_add_u32 vcc_lo, vcc_lo, 1
	v_mov_b32_e32 v211, vcc_lo
	v_readlane_b32 s100, v234, 34
	v_readlane_b32 s101, v234, 35
	s_mov_b32 m0, 0
	s_nop 4

.LBB0_566:
	v_readlane_b32 s8, v232, 13
	v_readlane_b32 s9, v232, 14
	s_and_b64 vcc, exec, s[8:9]
	s_cbranch_vccz .LBB0_586
	s_waitcnt vmcnt(0)
	s_waitcnt vmcnt(0) lgkmcnt(0)
	s_barrier
	s_and_saveexec_b64 s[0:1], s[86:87]
	s_cbranch_execz .LBB0_585
	s_mov_b64 s[34:35], exec
	v_mbcnt_lo_u32_b32 v0, s34, 0
	v_mbcnt_hi_u32_b32 v0, s35, v0
	v_cmp_eq_u32_e32 vcc, 0, v0
	s_and_saveexec_b64 s[8:9], vcc
	s_cbranch_execz .LBB0_570
	s_bcnt1_i32_b64 s34, s[34:35]
	v_mov_b32_e32 v1, s34
	v_readlane_b32 s34, v234, 34
	v_readlane_b32 s35, v234, 35
	s_nop 4
	global_atomic_add v210, v97, v1, s[34:35] sc0
.LBB0_570:
	s_or_b64 exec, exec, s[8:9]
	s_branch .LBB0_585
.LBB0_585:
	s_or_b64 exec, exec, s[0:1]
	s_mov_b32 s8, 1
	v_writelane_b32 v232, s8, 58
	s_mov_b64 s[0:1], -1
